# v110 + transposes: gridDim.x kept in s32 instead of one scalar load + wait per tile
# baseline (speedup 1.0000x reference)
.Lp0_parts:
	s_load_dword s32, s[74:75], 0x0
	s_waitcnt lgkmcnt(0)
	v_mov_b32_e32 v0, v179
	s_nop 0
	v_cmp_gt_i32_e32 vcc, 64, v0
	s_and_saveexec_b64 s[28:29], vcc
	s_cbranch_execz .LBB0_302
	s_waitcnt lgkmcnt(0)
	v_cvt_f32_i32_e32 v1, v0
	s_mov_b32 s0, 0x7f800000
	v_lshl_add_u32 v0, v0, 2, 0
	v_mul_f32_e32 v1, 0x3d000000, v1
	v_mul_f32_e64 v3, |v1|, 0.5
	v_fract_f32_e32 v4, v3
	v_add_f32_e32 v4, v4, v4
	v_cmp_neq_f32_e32 vcc, s0, v3
	v_cmp_gt_f32_e64 s[0:1], |v1|, 1.0
	v_and_b32_e32 v2, 0x7fffffff, v1
	v_cndmask_b32_e32 v3, 0, v4, vcc
	v_cndmask_b32_e64 v3, |v1|, v3, s[0:1]
	v_add_f32_e32 v4, v3, v3
	v_rndne_f32_e32 v4, v4
	v_fmac_f32_e32 v3, -0.5, v4
	v_cvt_i32_f32_e32 v5, v4
	v_mul_f32_e32 v4, v3, v3
	v_fmamk_f32 v6, v4, 0x3e75aa41, v180
	v_fmaak_f32 v6, v4, v6, 0x40234736
	v_fmaak_f32 v6, v4, v6, 0xc0a55e0e
	s_waitcnt vmcnt(0)
	v_mul_f32_e32 v8, v3, v4
	v_mul_f32_e32 v6, v8, v6
	v_fmac_f32_e32 v6, 0x40490fdb, v3
	v_fmamk_f32 v3, v4, 0x3d4be544, v182
	v_fmaak_f32 v3, v4, v3, 0xbfaad1da
	v_fmaak_f32 v3, v4, v3, 0x4081e0d3
	v_fmaak_f32 v3, v4, v3, 0xc09de9e6
	v_fma_f32 v3, v4, v3, 1.0
	v_and_b32_e32 v4, 1, v5
	v_and_b32_e32 v7, 2, v5
	v_cmp_eq_u32_e32 vcc, 0, v4
	v_cmp_eq_u32_e64 s[0:1], 0, v7
	v_lshlrev_b32_e32 v5, 30, v5
	v_cndmask_b32_e64 v4, -v6, v3, vcc
	v_cndmask_b32_e64 v4, -v4, v4, s[0:1]
	s_movk_i32 s0, 0x1f8
	v_cmp_class_f32_e64 s[0:1], v1, s0
	v_and_b32_e32 v5, 0x80000000, v5
	v_xor_b32_e32 v1, v2, v1
	v_cndmask_b32_e32 v3, v3, v6, vcc
	v_xor_b32_e32 v1, v1, v5
	v_xor_b32_e32 v1, v1, v3
	v_cndmask_b32_e64 v4, v226, v4, s[0:1]
	v_cndmask_b32_e64 v1, v226, v1, s[0:1]
	ds_write2st64_b32 v0, v4, v1 offset0:65 offset1:66

.LBB0_306:
	s_nop 0
	v_add_u32_e32 v0, 0x2080, v30
	s_barrier
	s_waitcnt vmcnt(2)
	ds_write2_b32 v30, v8, v9 offset1:1
	ds_write2_b32 v30, v10, v11 offset0:2 offset1:3
	s_waitcnt vmcnt(1)
	ds_write2_b32 v0, v12, v13 offset1:1
	v_add_u32_e32 v0, 0x2088, v30
	ds_write2_b32 v0, v14, v15 offset1:1
	s_waitcnt lgkmcnt(0)
	s_barrier
	s_mov_b32 s0, s32
	s_waitcnt lgkmcnt(0)
	s_add_i32 s2, s3, s0
	s_cmpk_gt_i32 s2, 0x1ff
	s_cselect_b64 s[0:1], -1, 0
	s_and_b64 vcc, exec, s[0:1]
	s_cbranch_vccnz .LBB0_309
	s_ashr_i32 s6, s2, 31
	s_lshr_b32 s6, s6, 28
	s_add_i32 s6, s2, s6
	s_and_b32 s7, s6, 0x3fffff0
	s_sub_i32 s7, s2, s7
	v_lshl_add_u32 v0, s7, 6, v23
	s_lshl_b32 s6, s6, 2
	v_ashrrev_i32_e32 v1, 31, v0
	v_readlane_b32 s56, v252, 10
	s_andn2_b32 s6, s6, 63
	v_lshlrev_b64 v[0:1], 13, v[0:1]
	v_readlane_b32 s60, v252, 14
	v_readlane_b32 s61, v252, 15
	s_ashr_i32 s7, s6, 31
	v_mov_b32_e32 v17, v177
	v_lshl_add_u64 v[0:1], s[60:61], 0, v[0:1]
	v_lshl_add_u64 v[0:1], s[6:7], 2, v[0:1]
	v_lshl_add_u64 v[0:1], v[0:1], 0, v[16:17]
	v_add_co_u32_e32 v2, vcc, 0x40000, v0
	v_readlane_b32 s62, v252, 16
	s_nop 0
	v_addc_co_u32_e32 v3, vcc, 0, v1, vcc
	global_load_dwordx4 v[8:11], v[0:1], off
	global_load_dwordx4 v[12:15], v[2:3], off
	v_readlane_b32 s63, v252, 17
	v_readlane_b32 s64, v252, 18
	v_readlane_b32 s65, v252, 19
	v_readlane_b32 s66, v252, 20
	v_readlane_b32 s67, v252, 21
	v_readlane_b32 s68, v252, 22
	v_readlane_b32 s69, v252, 23
	v_readlane_b32 s70, v252, 24
	v_readlane_b32 s71, v252, 25
	v_readlane_b32 s68, v255, 14
	v_readlane_b32 s70, v255, 12
	v_readlane_b32 s62, v255, 10
	v_readlane_b32 s64, v255, 6
	v_readlane_b32 s69, v255, 15
	v_readlane_b32 s71, v255, 13
	v_readlane_b32 s63, v255, 11
	v_readlane_b32 s65, v255, 7
	v_readlane_b32 s66, v255, 8
	v_readlane_b32 s67, v255, 9
	v_readlane_b32 s57, v252, 11
	v_readlane_b32 s58, v252, 12
	v_readlane_b32 s59, v252, 13
	s_cmpk_gt_i32 s3, 0x7f
	s_mov_b64 s[28:29], -1
	s_cbranch_scc1 .LBB0_310

.LBB0_325:
	s_nop 0
	v_add_u32_e32 v0, 0x2080, v30
	s_barrier
	s_waitcnt vmcnt(2)
	ds_write2_b32 v30, v8, v9 offset1:1
	ds_write2_b32 v30, v10, v11 offset0:2 offset1:3
	s_waitcnt vmcnt(1)
	ds_write2_b32 v0, v12, v13 offset1:1
	v_add_u32_e32 v0, 0x2088, v30
	ds_write2_b32 v0, v14, v15 offset1:1
	s_waitcnt lgkmcnt(0)
	s_barrier
	s_mov_b32 s0, s32
	s_waitcnt lgkmcnt(0)
	s_add_i32 s2, s3, s0
	s_cmpk_gt_i32 s2, 0xff
	s_cselect_b64 s[0:1], -1, 0
	s_and_b64 vcc, exec, s[0:1]
	s_cbranch_vccnz .LBB0_328
	s_ashr_i32 s6, s2, 31
	s_lshr_b32 s6, s6, 28
	s_add_i32 s6, s2, s6
	s_and_b32 s7, s6, 0x3fffff0
	s_sub_i32 s7, s2, s7
	v_lshl_add_u32 v0, s7, 6, v23
	s_lshl_b32 s6, s6, 2
	v_ashrrev_i32_e32 v1, 31, v0
	s_andn2_b32 s6, s6, 63
	v_lshlrev_b64 v[0:1], 12, v[0:1]
	v_lshl_add_u64 v[0:1], s[88:89], 0, v[0:1]
	s_ashr_i32 s7, s6, 31
	v_lshl_add_u64 v[0:1], s[6:7], 2, v[0:1]
	v_mov_b32_e32 v17, v177
	v_lshl_add_u64 v[0:1], v[0:1], 0, v[16:17]
	v_add_co_u32_e32 v2, vcc, 0x20000, v0
	s_nop 1
	v_addc_co_u32_e32 v3, vcc, 0, v1, vcc
	global_load_dwordx4 v[8:11], v[0:1], off
	global_load_dwordx4 v[12:15], v[2:3], off
	s_cmp_gt_i32 s3, -16
	s_mov_b64 s[28:29], -1
	s_cbranch_scc1 .LBB0_329

.LBB0_343:
	s_nop 0
	v_add_u32_e32 v0, 0x2080, v25
	s_barrier
	s_waitcnt vmcnt(2)
	ds_write2_b32 v25, v8, v9 offset1:1
	ds_write2_b32 v25, v10, v11 offset0:2 offset1:3
	s_waitcnt vmcnt(1)
	ds_write2_b32 v0, v12, v13 offset1:1
	v_add_u32_e32 v0, 0x2088, v25
	ds_write2_b32 v0, v14, v15 offset1:1
	s_waitcnt lgkmcnt(0)
	s_barrier
	s_mov_b32 s0, s32
	s_waitcnt lgkmcnt(0)
	s_add_i32 s2, s3, s0
	s_cmpk_gt_i32 s2, 0x3ff
	s_cselect_b64 s[0:1], -1, 0
	s_and_b64 vcc, exec, s[0:1]
	s_cbranch_vccnz .LBB0_346
	s_ashr_i32 s6, s2, 31
	s_lshr_b32 s6, s6, 28
	s_add_i32 s6, s2, s6
	s_and_b32 s7, s6, 0x3fffff0
	s_sub_i32 s7, s2, s7
	v_lshl_add_u32 v0, s7, 6, v17
	s_lshl_b32 s6, s6, 2
	v_ashrrev_i32_e32 v1, 31, v0
	v_readlane_b32 s44, v252, 0
	s_andn2_b32 s6, s6, 63
	v_lshlrev_b64 v[0:1], 14, v[0:1]
	v_readlane_b32 s45, v252, 1
	s_ashr_i32 s7, s6, 31
	v_mov_b32_e32 v19, v177
	v_lshl_add_u64 v[0:1], s[44:45], 0, v[0:1]
	v_lshl_add_u64 v[0:1], s[6:7], 2, v[0:1]
	v_lshl_add_u64 v[0:1], v[0:1], 0, v[18:19]
	v_add_co_u32_e32 v2, vcc, 0x80000, v0
	v_readlane_b32 s50, v252, 6
	s_nop 0
	v_addc_co_u32_e32 v3, vcc, 0, v1, vcc
	global_load_dwordx4 v[8:11], v[0:1], off
	global_load_dwordx4 v[12:15], v[2:3], off
	v_readlane_b32 s51, v252, 7
	v_readlane_b32 s50, v254, 13
	v_readlane_b32 s51, v254, 14
	v_readlane_b32 s46, v252, 2
	v_readlane_b32 s47, v252, 3
	v_readlane_b32 s48, v252, 4
	v_readlane_b32 s49, v252, 5
	s_cmp_gt_i32 s3, -16
	s_mov_b64 s[28:29], -1
	s_cbranch_scc1 .LBB0_347

.LBB0_365:
	s_nop 0
	v_add_u32_e32 v0, 0x2080, v30
	s_barrier
	s_waitcnt vmcnt(2)
	ds_write2_b32 v30, v8, v9 offset1:1
	ds_write2_b32 v30, v10, v11 offset0:2 offset1:3
	s_waitcnt vmcnt(1)
	ds_write2_b32 v0, v12, v13 offset1:1
	v_add_u32_e32 v0, 0x2088, v30
	ds_write2_b32 v0, v14, v15 offset1:1
	s_waitcnt lgkmcnt(0)
	s_barrier
	s_mov_b32 s0, s32
	s_waitcnt lgkmcnt(0)
	s_add_i32 s2, s3, s0
	s_cmpk_gt_i32 s2, 0x3ff
	s_cselect_b64 s[0:1], -1, 0
	s_and_b64 vcc, exec, s[0:1]
	s_cbranch_vccnz .LBB0_368
	s_ashr_i32 s6, s2, 31
	s_lshr_b32 s6, s6, 26
	s_add_i32 s6, s2, s6
	s_andn2_b32 s6, s6, 63
	s_sub_i32 s7, s2, s6
	v_lshl_add_u32 v0, s7, 6, v23
	v_ashrrev_i32_e32 v1, 31, v0
	v_readlane_b32 s44, v252, 0
	v_lshlrev_b64 v[0:1], 12, v[0:1]
	v_readlane_b32 s46, v252, 2
	v_readlane_b32 s47, v252, 3
	s_ashr_i32 s7, s6, 31
	v_mov_b32_e32 v17, v177
	v_lshl_add_u64 v[0:1], s[46:47], 0, v[0:1]
	v_lshl_add_u64 v[0:1], s[6:7], 2, v[0:1]
	v_lshl_add_u64 v[0:1], v[0:1], 0, v[16:17]
	v_add_co_u32_e32 v2, vcc, 0x20000, v0
	v_readlane_b32 s50, v252, 6
	s_nop 0
	v_addc_co_u32_e32 v3, vcc, 0, v1, vcc
	global_load_dwordx4 v[8:11], v[0:1], off
	global_load_dwordx4 v[12:15], v[2:3], off
	v_readlane_b32 s51, v252, 7
	v_readlane_b32 s50, v254, 13
	v_readlane_b32 s51, v254, 14
	v_readlane_b32 s45, v252, 1
	v_readlane_b32 s48, v252, 4
	v_readlane_b32 s49, v252, 5
	s_cmpk_gt_i32 s3, 0xffc0
	s_mov_b64 s[28:29], -1
	s_cbranch_scc1 .LBB0_369
